# P2 retention finalize: MIX stores of both query tiles widened to dwordx4 via v_permlane16_swap row pairs (16 dwordx2 -> 8 dwordx4 per wave)
# speedup vs baseline: 1.0137x; 1.0011x over previous
; __device__ __forceinline__ int lane_id() { return (int)__builtin_amdgcn_mbcnt_hi(~0u, __builtin_amdgcn_mbcnt_lo(~0u, 0u)); }
; __device__ __forceinline__ void ret_pair(LAS unsigned char* lds, const bf16_t* Z, bf16_t* MIX, int b, int h, int tA, int tB, const float* gain, int wid) {
;     ...
;     int lf = lane_id(); asm volatile("" : "+v"(lf)); const int q16f = lf & 15, quadf = (lf >> 4) & 3;
; #pragma unroll
;     for (int which = 0; which < 2; ++which) {
;         f32x4 (&O)[8] = which ? OB : OA;
;         float ss = 0.f;
; #pragma unroll
;         for (int eb = 0; eb < 8; ++eb)
; #pragma unroll
;             for (int i = 0; i < 4; ++i) ss += O[eb][i] * O[eb][i];
;         ss = quad_sum(ss);
;         const float r = rsqrtf(ss * (1.0f / 128.0f) + EPS);
;         const int row = (which ? rowB0 : rowA0) + q16f;
;         const bf16_t* gp = Z + (size_t)row * DIN + gcol + 4 * quadf;
;         bf16_t* op = MIX + (size_t)row * DM + 128 * h + 4 * quadf;
; #pragma unroll
;         for (int eb = 0; eb < 8; ++eb) {
;             const u32x2 gw = *(const u32x2*)(gp + 16 * eb);
;             const f32x4 gn = *(const f32x4*)(gain + 16 * eb + 4 * quadf);
.LBB0_640:
	s_lshl_b32 s0, s80, 2
	v_readlane_b32 s1, v254, 24
	s_add_u32 s0, s1, s0
	v_readlane_b32 s1, v254, 23
	v_readlane_b32 s2, v255, 3
	s_waitcnt lgkmcnt(0)
	v_mov_b32_e32 v4, v183
	s_addc_u32 s1, s1, 0
	s_add_i32 s4, s2, 1
	s_add_u32 s2, s30, s86
	v_and_b32_e32 v93, 15, v4
	v_lshrrev_b32_e32 v4, 2, v4
	s_addc_u32 s3, s31, 0
	v_and_b32_e32 v4, 12, v4
	v_lshlrev_b32_e32 v180, 1, v4
	v_lshlrev_b32_e32 v4, 2, v4
	v_mov_b32_e32 v5, v181
	v_or_b32_e32 v32, s5, v93
	v_mov_b64_e32 v[6:7], s[2:3]
	v_lshl_add_u64 v[4:5], s[0:1], 0, v[4:5]
	v_readlane_b32 s3, v255, 7
	s_mov_b64 s[6:7], 0x1000
	v_mad_i64_i32 v[8:9], vcc, v32, s36, v[6:7]
	v_mov_b32_e32 v29, v181
	v_or_b32_e32 v30, s3, v93
	v_lshl_add_u64 v[10:11], v[8:9], 0, v[180:181]
	v_mad_i64_i32 v[6:7], vcc, v30, s36, v[6:7]
	v_lshl_add_u64 v[10:11], v[10:11], 0, s[6:7]
	v_lshl_add_u64 v[6:7], v[6:7], 0, v[180:181]
	s_add_u32 s0, s88, s86
	s_addc_u32 s1, s89, 0
	v_lshl_add_u64 v[6:7], v[6:7], 0, s[6:7]
	global_load_dwordx4 v[96:99], v[4:5], off
	global_load_dwordx2 v[134:135], v[10:11], off
	global_load_dwordx2 v[150:151], v[6:7], off
	global_load_dwordx4 v[100:103], v[4:5], off offset:64
	global_load_dwordx2 v[136:137], v[10:11], off offset:32
	global_load_dwordx2 v[152:153], v[6:7], off offset:32
	global_load_dwordx4 v[104:107], v[4:5], off offset:128
	global_load_dwordx2 v[138:139], v[10:11], off offset:64
	global_load_dwordx2 v[154:155], v[6:7], off offset:64
	global_load_dwordx4 v[108:111], v[4:5], off offset:192
	global_load_dwordx2 v[140:141], v[10:11], off offset:96
	global_load_dwordx2 v[156:157], v[6:7], off offset:96
	global_load_dwordx4 v[112:115], v[4:5], off offset:256
	global_load_dwordx2 v[142:143], v[10:11], off offset:128
	global_load_dwordx2 v[158:159], v[6:7], off offset:128
	global_load_dwordx4 v[116:119], v[4:5], off offset:320
	global_load_dwordx2 v[144:145], v[10:11], off offset:160
	global_load_dwordx2 v[160:161], v[6:7], off offset:160
	global_load_dwordx4 v[120:123], v[4:5], off offset:384
	global_load_dwordx2 v[146:147], v[10:11], off offset:192
	global_load_dwordx2 v[162:163], v[6:7], off offset:192
	global_load_dwordx4 v[124:127], v[4:5], off offset:448
	global_load_dwordx2 v[148:149], v[10:11], off offset:224
	global_load_dwordx2 v[164:165], v[6:7], off offset:224
	v_lshl_add_u64 v[8:9], s[0:1], 0, v[180:181]
	v_mov_b32_e32 v28, v32
	v_mov_b32_e32 v31, v181
	v_lshlrev_b64 v[28:29], 12, v[28:29]
	v_lshlrev_b64 v[30:31], 12, v[30:31]
	v_lshl_add_u64 v[166:167], v[8:9], 0, v[28:29]
	v_lshl_add_u64 v[168:169], v[8:9], 0, v[30:31]
	v_mul_f32_e32 v33, v81, v81
	v_fmac_f32_e32 v33, v80, v80
	v_fmac_f32_e32 v33, v82, v82
	v_fmac_f32_e32 v33, v83, v83
	v_fmac_f32_e32 v33, v76, v76
	v_fmac_f32_e32 v33, v77, v77
	v_fmac_f32_e32 v33, v78, v78
	v_fmac_f32_e32 v33, v79, v79
	v_fmac_f32_e32 v33, v72, v72
	v_fmac_f32_e32 v33, v73, v73
	v_fmac_f32_e32 v33, v74, v74
	v_fmac_f32_e32 v33, v75, v75
	v_fmac_f32_e32 v33, v68, v68
	v_fmac_f32_e32 v33, v69, v69
	v_fmac_f32_e32 v33, v70, v70
	v_fmac_f32_e32 v33, v71, v71
	v_fmac_f32_e32 v33, v64, v64
	v_fmac_f32_e32 v33, v65, v65
	v_fmac_f32_e32 v33, v66, v66
	v_fmac_f32_e32 v33, v67, v67
	v_fmac_f32_e32 v33, v60, v60
	v_fmac_f32_e32 v33, v61, v61
	v_fmac_f32_e32 v33, v62, v62
	v_fmac_f32_e32 v33, v63, v63
	v_pk_mul_f32 v[84:85], v[56:57], v[56:57]
	v_pk_mul_f32 v[8:9], v[58:59], v[58:59]
	v_add_f32_e32 v33, v84, v33
	v_add_f32_e32 v33, v85, v33
	v_add_f32_e32 v8, v8, v33
	v_add_f32_e32 v33, v9, v8
	v_pk_mul_f32 v[84:85], v[52:53], v[52:53]
	v_pk_mul_f32 v[8:9], v[54:55], v[54:55]
	v_add_f32_e32 v33, v84, v33
	v_add_f32_e32 v33, v85, v33
	v_add_f32_e32 v8, v8, v33
	v_add_f32_e32 v33, v9, v8
	ds_swizzle_b32 v84, v33 offset:swizzle(SWAP,16)
	v_pk_mul_f32 v[90:91], v[16:17], v[16:17]
	v_pk_mul_f32 v[88:89], v[18:19], v[18:19]
	s_waitcnt lgkmcnt(0)
	v_add_f32_e32 v85, v33, v84
	v_mul_f32_e32 v84, v49, v49
	v_fmac_f32_e32 v84, v48, v48
	v_fmac_f32_e32 v84, v50, v50
	v_fmac_f32_e32 v84, v51, v51
	v_fmac_f32_e32 v84, v44, v44
	v_fmac_f32_e32 v84, v45, v45
	v_fmac_f32_e32 v84, v46, v46
	v_fmac_f32_e32 v84, v47, v47
	v_fmac_f32_e32 v84, v40, v40
	v_fmac_f32_e32 v84, v41, v41
	v_fmac_f32_e32 v84, v42, v42
	v_fmac_f32_e32 v84, v43, v43
	v_fmac_f32_e32 v84, v36, v36
	v_fmac_f32_e32 v84, v37, v37
	v_fmac_f32_e32 v84, v38, v38
	v_fmac_f32_e32 v84, v39, v39
	v_fmac_f32_e32 v84, v24, v24
	v_fmac_f32_e32 v84, v25, v25
	v_fmac_f32_e32 v84, v26, v26
	v_fmac_f32_e32 v84, v27, v27
	v_fmac_f32_e32 v84, v20, v20
	v_fmac_f32_e32 v84, v21, v21
	v_fmac_f32_e32 v84, v22, v22
	v_fmac_f32_e32 v84, v23, v23
	v_add_f32_e32 v84, v90, v84
	v_add_f32_e32 v84, v91, v84
	v_add_f32_e32 v84, v88, v84
	v_add_f32_e32 v84, v89, v84
	v_pk_mul_f32 v[90:91], v[12:13], v[12:13]
	v_pk_mul_f32 v[88:89], v[14:15], v[14:15]
	v_add_f32_e32 v84, v90, v84
	v_add_f32_e32 v84, v91, v84
	v_add_f32_e32 v84, v88, v84
	v_add_f32_e32 v84, v89, v84
	ds_swizzle_b32 v86, v84 offset:swizzle(SWAP,16)
	v_mov_b32_e32 v87, v85
	s_nop 1
	v_permlane32_swap_b32_e32 v85, v87
	s_waitcnt lgkmcnt(0)
	v_add_f32_e32 v84, v84, v86
	v_mov_b32_e32 v86, v84
	s_nop 1
	v_permlane32_swap_b32_e32 v84, v86
	v_pk_add_f32 v[84:85], v[84:85], v[86:87]
	s_brev_b32 s0, 60
	v_mov_b32_e32 v34, 0x358637bd
	v_pk_fma_f32 v[84:85], v[84:85], s[0:1], v[34:35] op_sel_hi:[1,0,0]
	s_mov_b32 s2, 0x800000
	v_mul_f32_e32 v34, 0x4b800000, v85
	v_cmp_gt_f32_e32 vcc, s2, v85
	v_mul_f32_e32 v35, 0x4b800000, v84
	v_cmp_gt_f32_e64 s[0:1], s2, v84
	v_cndmask_b32_e32 v34, v85, v34, vcc
	v_rsq_f32_e32 v85, v34
	v_cndmask_b32_e64 v35, v84, v35, s[0:1]
	v_rsq_f32_e32 v84, v35
	v_mul_f32_e32 v92, 0x45800000, v85
	v_cndmask_b32_e32 v92, v85, v92, vcc
	v_mul_f32_e32 v94, 0x45800000, v84
	v_cndmask_b32_e64 v94, v84, v94, s[0:1]
	s_mov_b32 s87, s27
	s_mov_b32 m0, s90
	s_mov_b32 s42, 0x800000
	s_mov_b32 s5, 0
	s_waitcnt vmcnt(0)
; __device__ __forceinline__ unsigned cvtpk(float lo, float hi) { f32x2 v = {lo, hi}; bf16x2_t b = __builtin_convertvector(v, bf16x2_t); return __builtin_bit_cast(unsigned, b); }
; __device__ __forceinline__ float bflo(unsigned u) { return __uint_as_float(u << 16); }
; __device__ __forceinline__ float bfhi(unsigned u) { return __uint_as_float(u & 0xffff0000u); }
; __device__ __forceinline__ void ret_pair(LAS unsigned char* lds, const bf16_t* Z, bf16_t* MIX, int b, int h, int tA, int tB, const float* gain, int wid) {
;     ...
;     for (int which = 0; which < 2; ++which) {
;         f32x4 (&O)[8] = which ? OB : OA;
;         float ss = 0.f;
; #pragma unroll
;         for (int eb = 0; eb < 8; ++eb)
; #pragma unroll
;             for (int i = 0; i < 4; ++i) ss += O[eb][i] * O[eb][i];
;         ss = quad_sum(ss);
;         const float r = rsqrtf(ss * (1.0f / 128.0f) + EPS);
;         const int row = (which ? rowB0 : rowA0) + q16f;
;         const bf16_t* gp = Z + (size_t)row * DIN + gcol + 4 * quadf;
;         bf16_t* op = MIX + (size_t)row * DM + 128 * h + 4 * quadf;
; #pragma unroll
;         for (int eb = 0; eb < 8; ++eb) {
;             const u32x2 gw = *(const u32x2*)(gp + 16 * eb);
;             const f32x4 gn = *(const f32x4*)(gain + 16 * eb + 4 * quadf);
;             u32x2 w; w.x = cvtpk(O[eb][0] * r * gn.x * bflo(gw.x), O[eb][1] * r * gn.y * bfhi(gw.x));
;             w.y = cvtpk(O[eb][2] * r * gn.z * bflo(gw.y), O[eb][3] * r * gn.w * bfhi(gw.y));
;             *(u32x2*)(op + 16 * eb) = w;
;         }
	v_mbcnt_lo_u32_b32 v178, -1, 0
	v_mbcnt_hi_u32_b32 v178, -1, v178
	v_and_b32_e32 v178, 16, v178
	v_lshrrev_b32_e32 v179, 1, v178
	v_add_u32_e32 v178, v178, v179
	v_mov_b32_e32 v179, 0
	v_lshl_add_u64 v[174:175], v[166:167], 0, v[178:179]
	v_lshl_add_u64 v[176:177], v[168:169], 0, v[178:179]
	v_pk_mul_f32 v[80:81], v[80:81], v[92:93] op_sel_hi:[1,0]
	v_pk_mul_f32 v[82:83], v[82:83], v[92:93] op_sel_hi:[1,0]
	v_lshlrev_b32_e32 v28, 16, v134
	v_and_b32_e32 v29, 0xffff0000, v134
	v_lshlrev_b32_e32 v30, 16, v135
	v_and_b32_e32 v31, 0xffff0000, v135
	v_pk_mul_f32 v[80:81], v[96:97], v[80:81]
	v_pk_mul_f32 v[82:83], v[98:99], v[82:83]
	v_pk_mul_f32 v[80:81], v[80:81], v[28:29]
	v_pk_mul_f32 v[82:83], v[82:83], v[30:31]
	v_cvt_pk_bf16_f32 v80, v80, v81
	v_cvt_pk_bf16_f32 v81, v82, v83
	v_pk_mul_f32 v[76:77], v[76:77], v[92:93] op_sel_hi:[1,0]
	v_pk_mul_f32 v[78:79], v[78:79], v[92:93] op_sel_hi:[1,0]
	v_lshlrev_b32_e32 v170, 16, v136
	v_and_b32_e32 v171, 0xffff0000, v136
	v_lshlrev_b32_e32 v172, 16, v137
	v_and_b32_e32 v173, 0xffff0000, v137
	v_pk_mul_f32 v[76:77], v[100:101], v[76:77]
	v_pk_mul_f32 v[78:79], v[102:103], v[78:79]
	v_pk_mul_f32 v[76:77], v[76:77], v[170:171]
	v_pk_mul_f32 v[78:79], v[78:79], v[172:173]
	v_cvt_pk_bf16_f32 v82, v76, v77
	v_cvt_pk_bf16_f32 v83, v78, v79
	s_nop 1
	v_permlane16_swap_b32_e32 v80, v82
	v_permlane16_swap_b32_e32 v81, v83
	global_store_dwordx4 v[174:175], v[80:83], off
	v_pk_mul_f32 v[48:49], v[48:49], v[94:95] op_sel_hi:[1,0]
	v_pk_mul_f32 v[50:51], v[50:51], v[94:95] op_sel_hi:[1,0]
	v_lshlrev_b32_e32 v28, 16, v150
	v_and_b32_e32 v29, 0xffff0000, v150
	v_lshlrev_b32_e32 v30, 16, v151
	v_and_b32_e32 v31, 0xffff0000, v151
	v_pk_mul_f32 v[48:49], v[96:97], v[48:49]
	v_pk_mul_f32 v[50:51], v[98:99], v[50:51]
	v_pk_mul_f32 v[48:49], v[48:49], v[28:29]
	v_pk_mul_f32 v[50:51], v[50:51], v[30:31]
	v_cvt_pk_bf16_f32 v48, v48, v49
	v_cvt_pk_bf16_f32 v49, v50, v51
	v_pk_mul_f32 v[44:45], v[44:45], v[94:95] op_sel_hi:[1,0]
	v_pk_mul_f32 v[46:47], v[46:47], v[94:95] op_sel_hi:[1,0]
	v_lshlrev_b32_e32 v170, 16, v152
	v_and_b32_e32 v171, 0xffff0000, v152
	v_lshlrev_b32_e32 v172, 16, v153
	v_and_b32_e32 v173, 0xffff0000, v153
	v_pk_mul_f32 v[44:45], v[100:101], v[44:45]
	v_pk_mul_f32 v[46:47], v[102:103], v[46:47]
	v_pk_mul_f32 v[44:45], v[44:45], v[170:171]
	v_pk_mul_f32 v[46:47], v[46:47], v[172:173]
	v_cvt_pk_bf16_f32 v50, v44, v45
	v_cvt_pk_bf16_f32 v51, v46, v47
	s_nop 1
	v_permlane16_swap_b32_e32 v48, v50
	v_permlane16_swap_b32_e32 v49, v51
	global_store_dwordx4 v[176:177], v[48:51], off
	v_pk_mul_f32 v[72:73], v[72:73], v[92:93] op_sel_hi:[1,0]
	v_pk_mul_f32 v[74:75], v[74:75], v[92:93] op_sel_hi:[1,0]
	v_lshlrev_b32_e32 v28, 16, v138
	v_and_b32_e32 v29, 0xffff0000, v138
	v_lshlrev_b32_e32 v30, 16, v139
	v_and_b32_e32 v31, 0xffff0000, v139
	v_pk_mul_f32 v[72:73], v[104:105], v[72:73]
	v_pk_mul_f32 v[74:75], v[106:107], v[74:75]
	v_pk_mul_f32 v[72:73], v[72:73], v[28:29]
	v_pk_mul_f32 v[74:75], v[74:75], v[30:31]
	v_cvt_pk_bf16_f32 v72, v72, v73
	v_cvt_pk_bf16_f32 v73, v74, v75
	v_pk_mul_f32 v[68:69], v[68:69], v[92:93] op_sel_hi:[1,0]
	v_pk_mul_f32 v[70:71], v[70:71], v[92:93] op_sel_hi:[1,0]
	v_lshlrev_b32_e32 v170, 16, v140
	v_and_b32_e32 v171, 0xffff0000, v140
	v_lshlrev_b32_e32 v172, 16, v141
	v_and_b32_e32 v173, 0xffff0000, v141
	v_pk_mul_f32 v[68:69], v[108:109], v[68:69]
	v_pk_mul_f32 v[70:71], v[110:111], v[70:71]
	v_pk_mul_f32 v[68:69], v[68:69], v[170:171]
	v_pk_mul_f32 v[70:71], v[70:71], v[172:173]
	v_cvt_pk_bf16_f32 v74, v68, v69
	v_cvt_pk_bf16_f32 v75, v70, v71
	s_nop 1
	v_permlane16_swap_b32_e32 v72, v74
	v_permlane16_swap_b32_e32 v73, v75
	global_store_dwordx4 v[174:175], v[72:75], off offset:64
	v_pk_mul_f32 v[40:41], v[40:41], v[94:95] op_sel_hi:[1,0]
	v_pk_mul_f32 v[42:43], v[42:43], v[94:95] op_sel_hi:[1,0]
	v_lshlrev_b32_e32 v28, 16, v154
	v_and_b32_e32 v29, 0xffff0000, v154
	v_lshlrev_b32_e32 v30, 16, v155
	v_and_b32_e32 v31, 0xffff0000, v155
	v_pk_mul_f32 v[40:41], v[104:105], v[40:41]
	v_pk_mul_f32 v[42:43], v[106:107], v[42:43]
	v_pk_mul_f32 v[40:41], v[40:41], v[28:29]
	v_pk_mul_f32 v[42:43], v[42:43], v[30:31]
	v_cvt_pk_bf16_f32 v40, v40, v41
	v_cvt_pk_bf16_f32 v41, v42, v43
	v_pk_mul_f32 v[36:37], v[36:37], v[94:95] op_sel_hi:[1,0]
	v_pk_mul_f32 v[38:39], v[38:39], v[94:95] op_sel_hi:[1,0]
	v_lshlrev_b32_e32 v170, 16, v156
	v_and_b32_e32 v171, 0xffff0000, v156
	v_lshlrev_b32_e32 v172, 16, v157
	v_and_b32_e32 v173, 0xffff0000, v157
	v_pk_mul_f32 v[36:37], v[108:109], v[36:37]
	v_pk_mul_f32 v[38:39], v[110:111], v[38:39]
	v_pk_mul_f32 v[36:37], v[36:37], v[170:171]
	v_pk_mul_f32 v[38:39], v[38:39], v[172:173]
	v_cvt_pk_bf16_f32 v42, v36, v37
	v_cvt_pk_bf16_f32 v43, v38, v39
	s_nop 1
	v_permlane16_swap_b32_e32 v40, v42
	v_permlane16_swap_b32_e32 v41, v43
	global_store_dwordx4 v[176:177], v[40:43], off offset:64
	v_pk_mul_f32 v[64:65], v[64:65], v[92:93] op_sel_hi:[1,0]
	v_pk_mul_f32 v[66:67], v[66:67], v[92:93] op_sel_hi:[1,0]
	v_lshlrev_b32_e32 v28, 16, v142
	v_and_b32_e32 v29, 0xffff0000, v142
	v_lshlrev_b32_e32 v30, 16, v143
	v_and_b32_e32 v31, 0xffff0000, v143
	v_pk_mul_f32 v[64:65], v[112:113], v[64:65]
	v_pk_mul_f32 v[66:67], v[114:115], v[66:67]
	v_pk_mul_f32 v[64:65], v[64:65], v[28:29]
; __device__ __forceinline__ unsigned cvtpk(float lo, float hi) { f32x2 v = {lo, hi}; bf16x2_t b = __builtin_convertvector(v, bf16x2_t); return __builtin_bit_cast(unsigned, b); }
; __device__ __forceinline__ float bflo(unsigned u) { return __uint_as_float(u << 16); }
; __device__ __forceinline__ float bfhi(unsigned u) { return __uint_as_float(u & 0xffff0000u); }
; __device__ __forceinline__ void ret_pair(LAS unsigned char* lds, const bf16_t* Z, bf16_t* MIX, int b, int h, int tA, int tB, const float* gain, int wid) {
;     ...
;         for (int eb = 0; eb < 8; ++eb) {
;             const u32x2 gw = *(const u32x2*)(gp + 16 * eb);
;             const f32x4 gn = *(const f32x4*)(gain + 16 * eb + 4 * quadf);
;             u32x2 w; w.x = cvtpk(O[eb][0] * r * gn.x * bflo(gw.x), O[eb][1] * r * gn.y * bfhi(gw.x));
;             w.y = cvtpk(O[eb][2] * r * gn.z * bflo(gw.y), O[eb][3] * r * gn.w * bfhi(gw.y));
;             *(u32x2*)(op + 16 * eb) = w;
;         }
; __global__ void __launch_bounds__(NWAVES * 64, 2) fwd(Args args) {
;     ...
;         for (int pi = vcu; pi < 256; pi += G) {
;             const int bh = pi >> 3, tp = pi & 7, b = bh >> 3, h = bh & 7;
;             attn_item<true>(lds, Z, MIX, b, h, 15 - tp, lam, shift, subln, 0, wid, 0);
;             ret_pair(lds, Z, MIX, b, h, 15 - tp, tp, ret_gn + 128 * h, wid);
;             attn_item<true>(lds, Z, MIX, b, h, tp, lam, shift, subln, 0, wid, 0);
	v_pk_mul_f32 v[66:67], v[66:67], v[30:31]
	v_cvt_pk_bf16_f32 v64, v64, v65
	v_cvt_pk_bf16_f32 v65, v66, v67
	v_pk_mul_f32 v[60:61], v[60:61], v[92:93] op_sel_hi:[1,0]
	v_pk_mul_f32 v[62:63], v[62:63], v[92:93] op_sel_hi:[1,0]
	v_lshlrev_b32_e32 v170, 16, v144
	v_and_b32_e32 v171, 0xffff0000, v144
	v_lshlrev_b32_e32 v172, 16, v145
	v_and_b32_e32 v173, 0xffff0000, v145
	v_pk_mul_f32 v[60:61], v[116:117], v[60:61]
	v_pk_mul_f32 v[62:63], v[118:119], v[62:63]
	v_pk_mul_f32 v[60:61], v[60:61], v[170:171]
	v_pk_mul_f32 v[62:63], v[62:63], v[172:173]
	v_cvt_pk_bf16_f32 v66, v60, v61
	v_cvt_pk_bf16_f32 v67, v62, v63
	s_nop 1
	v_permlane16_swap_b32_e32 v64, v66
	v_permlane16_swap_b32_e32 v65, v67
	global_store_dwordx4 v[174:175], v[64:67], off offset:128
	v_pk_mul_f32 v[24:25], v[24:25], v[94:95] op_sel_hi:[1,0]
	v_pk_mul_f32 v[26:27], v[26:27], v[94:95] op_sel_hi:[1,0]
	v_lshlrev_b32_e32 v28, 16, v158
	v_and_b32_e32 v29, 0xffff0000, v158
	v_lshlrev_b32_e32 v30, 16, v159
	v_and_b32_e32 v31, 0xffff0000, v159
	v_pk_mul_f32 v[24:25], v[112:113], v[24:25]
	v_pk_mul_f32 v[26:27], v[114:115], v[26:27]
	v_pk_mul_f32 v[24:25], v[24:25], v[28:29]
	v_pk_mul_f32 v[26:27], v[26:27], v[30:31]
	v_cvt_pk_bf16_f32 v24, v24, v25
	v_cvt_pk_bf16_f32 v25, v26, v27
	v_pk_mul_f32 v[20:21], v[20:21], v[94:95] op_sel_hi:[1,0]
	v_pk_mul_f32 v[22:23], v[22:23], v[94:95] op_sel_hi:[1,0]
	v_lshlrev_b32_e32 v170, 16, v160
	v_and_b32_e32 v171, 0xffff0000, v160
	v_lshlrev_b32_e32 v172, 16, v161
	v_and_b32_e32 v173, 0xffff0000, v161
	v_pk_mul_f32 v[20:21], v[116:117], v[20:21]
	v_pk_mul_f32 v[22:23], v[118:119], v[22:23]
	v_pk_mul_f32 v[20:21], v[20:21], v[170:171]
	v_pk_mul_f32 v[22:23], v[22:23], v[172:173]
	v_cvt_pk_bf16_f32 v26, v20, v21
	v_cvt_pk_bf16_f32 v27, v22, v23
	s_nop 1
	v_permlane16_swap_b32_e32 v24, v26
	v_permlane16_swap_b32_e32 v25, v27
	global_store_dwordx4 v[176:177], v[24:27], off offset:128
	v_pk_mul_f32 v[56:57], v[56:57], v[92:93] op_sel_hi:[1,0]
	v_pk_mul_f32 v[58:59], v[58:59], v[92:93] op_sel_hi:[1,0]
	v_lshlrev_b32_e32 v28, 16, v146
	v_and_b32_e32 v29, 0xffff0000, v146
	v_lshlrev_b32_e32 v30, 16, v147
	v_and_b32_e32 v31, 0xffff0000, v147
	v_pk_mul_f32 v[56:57], v[120:121], v[56:57]
	v_pk_mul_f32 v[58:59], v[122:123], v[58:59]
	v_pk_mul_f32 v[56:57], v[56:57], v[28:29]
	v_pk_mul_f32 v[58:59], v[58:59], v[30:31]
	v_cvt_pk_bf16_f32 v56, v56, v57
	v_cvt_pk_bf16_f32 v57, v58, v59
	v_pk_mul_f32 v[52:53], v[52:53], v[92:93] op_sel_hi:[1,0]
	v_pk_mul_f32 v[54:55], v[54:55], v[92:93] op_sel_hi:[1,0]
	v_lshlrev_b32_e32 v170, 16, v148
	v_and_b32_e32 v171, 0xffff0000, v148
	v_lshlrev_b32_e32 v172, 16, v149
	v_and_b32_e32 v173, 0xffff0000, v149
	v_pk_mul_f32 v[52:53], v[124:125], v[52:53]
	v_pk_mul_f32 v[54:55], v[126:127], v[54:55]
	v_pk_mul_f32 v[52:53], v[52:53], v[170:171]
	v_pk_mul_f32 v[54:55], v[54:55], v[172:173]
	v_cvt_pk_bf16_f32 v58, v52, v53
	v_cvt_pk_bf16_f32 v59, v54, v55
	s_nop 1
	v_permlane16_swap_b32_e32 v56, v58
	v_permlane16_swap_b32_e32 v57, v59
	global_store_dwordx4 v[174:175], v[56:59], off offset:192
	v_pk_mul_f32 v[16:17], v[16:17], v[94:95] op_sel_hi:[1,0]
	v_pk_mul_f32 v[18:19], v[18:19], v[94:95] op_sel_hi:[1,0]
	v_lshlrev_b32_e32 v28, 16, v162
	v_and_b32_e32 v29, 0xffff0000, v162
	v_lshlrev_b32_e32 v30, 16, v163
	v_and_b32_e32 v31, 0xffff0000, v163
	v_pk_mul_f32 v[16:17], v[120:121], v[16:17]
	v_pk_mul_f32 v[18:19], v[122:123], v[18:19]
	v_pk_mul_f32 v[16:17], v[16:17], v[28:29]
	v_pk_mul_f32 v[18:19], v[18:19], v[30:31]
	v_cvt_pk_bf16_f32 v16, v16, v17
	v_cvt_pk_bf16_f32 v17, v18, v19
	v_pk_mul_f32 v[12:13], v[12:13], v[94:95] op_sel_hi:[1,0]
	v_pk_mul_f32 v[14:15], v[14:15], v[94:95] op_sel_hi:[1,0]
	v_lshlrev_b32_e32 v170, 16, v164
	v_and_b32_e32 v171, 0xffff0000, v164
	v_lshlrev_b32_e32 v172, 16, v165
	v_and_b32_e32 v173, 0xffff0000, v165
	v_pk_mul_f32 v[12:13], v[124:125], v[12:13]
	v_pk_mul_f32 v[14:15], v[126:127], v[14:15]
	v_pk_mul_f32 v[12:13], v[12:13], v[170:171]
	v_pk_mul_f32 v[14:15], v[14:15], v[172:173]
	v_cvt_pk_bf16_f32 v18, v12, v13
	v_cvt_pk_bf16_f32 v19, v14, v15
	s_nop 1
	v_permlane16_swap_b32_e32 v16, v18
	v_permlane16_swap_b32_e32 v17, v19
	global_store_dwordx4 v[176:177], v[16:19], off offset:192
	s_nop 1
	v_readlane_b32 s17, v254, 44
	v_readlane_b32 s38, v254, 45
	v_readlane_b32 s39, v254, 46
	v_readlane_b32 s18, v254, 47
	v_readlane_b32 s40, v254, 48
	v_readlane_b32 s41, v254, 49
	v_readlane_b32 s43, v254, 50
	v_readlane_b32 s28, v254, 36
	v_readlane_b32 s30, v254, 37
	v_readlane_b32 s31, v254, 38
	v_readlane_b32 s88, v254, 39
	v_readlane_b32 s89, v254, 40
	v_readlane_b32 s29, v254, 41
	v_readlane_b32 s34, v254, 42
	v_readlane_b32 s35, v254, 43
	v_readlane_b32 s66, v254, 33
	v_readlane_b32 s84, v254, 34
	v_readlane_b32 s85, v254, 35
	v_readlane_b32 s78, v254, 32
	s_mov_b32 s27, 0
	s_movk_i32 s36, 0x3800
	s_mov_b64 s[14:15], 0x1800
	s_movk_i32 s16, 0x1000
	s_movk_i32 s37, 0x1c00
	s_mov_b64 s[96:97], 0x80
	s_movk_i32 s67, 0xe0
	s_movk_i32 s73, 0x60
	s_movk_i32 s74, 0x80
	s_movk_i32 s75, 0xa0
	s_movk_i32 s79, 0xc0
	s_mov_b64 s[92:93], 0x3000
	s_mov_b32 s42, 0x800000
	v_readlane_b32 s44, v255, 2
	v_readlane_b32 s2, v254, 51
	s_mov_b32 s98, 1
	s_mov_b32 s99, 0x01234567
	s_branch .LBB0_565
